# plus: cmp2 w2 staging loads batched; sel-loop row-sum adds interleaved under the PV MFMAs (late waves defer the sum with their PV)
# speedup vs baseline: 1.0118x; 1.0105x over previous
.LBB0_1004:
	s_bfe_u32 s22, s21, 0x30005
	s_cmpk_gt_u32 s21, 0xff
	s_cselect_b64 s[12:13], -1, 0
	s_and_b32 s14, s21, 0xffffff00
	s_add_i32 s16, s14, s18
	s_cmpk_lt_u32 s21, 0x100
	s_mov_b32 s14, 0x1c700000
	s_cselect_b32 s17, s14, 0x1cf00000
	s_movk_i32 s14, 0x48
	s_cselect_b32 s14, s14, 0x58
	s_add_u32 s14, s2, s14
	s_addc_u32 s15, s3, 0
	s_load_dwordx2 s[14:15], s[14:15], 0x0
	s_waitcnt lgkmcnt(0)
	s_barrier
	s_add_u32 s14, s14, s10
	s_addc_u32 s15, s15, s11
	v_lshl_add_u64 v[12:13], v[4:5], 4, s[14:15]
	global_load_dwordx4 v[0:3], v[12:13], off
	s_movk_i32 s14, 0x6000
	v_add_co_u32_e32 v116, vcc, s69, v12
	s_nop 1
	v_addc_co_u32_e32 v117, vcc, 0, v13, vcc
	global_load_dwordx4 v[120:123], v[116:117], off
	v_add_co_u32_e32 v118, vcc, s81, v12
	s_nop 1
	v_addc_co_u32_e32 v119, vcc, 0, v13, vcc
	global_load_dwordx4 v[124:127], v[118:119], off
	v_add_co_u32_e32 v116, vcc, s14, v12
	s_mov_b32 s14, 0xa000
	s_nop 0
	v_addc_co_u32_e32 v117, vcc, 0, v13, vcc
	global_load_dwordx4 v[128:131], v[116:117], off
	v_add_co_u32_e32 v118, vcc, s84, v12
	s_nop 1
	v_addc_co_u32_e32 v119, vcc, 0, v13, vcc
	global_load_dwordx4 v[132:135], v[118:119], off
	v_add_co_u32_e32 v116, vcc, s14, v12
	s_mov_b32 s14, 0xe000
	s_nop 0
	v_addc_co_u32_e32 v117, vcc, 0, v13, vcc
	global_load_dwordx4 v[136:139], v[116:117], off
	v_add_co_u32_e32 v118, vcc, s85, v12
	s_nop 1
	v_addc_co_u32_e32 v119, vcc, 0, v13, vcc
	global_load_dwordx4 v[140:143], v[118:119], off
	v_add_co_u32_e32 v116, vcc, s14, v12
	s_add_u32 s14, s4, s17
	s_nop 0
	v_addc_co_u32_e32 v117, vcc, 0, v13, vcc
	global_load_dwordx4 v[144:147], v[116:117], off
	s_addc_u32 s15, s5, 0
	s_lshl_b32 s23, s21, 4
	s_and_b32 s23, s23, 0x1f0
	v_add_u32_e32 v12, s23, v17
	s_lshl_b32 s76, s22, 9
	v_ashrrev_i32_e32 v13, 31, v12
	s_ashr_i32 s17, s16, 31
	s_waitcnt vmcnt(7)
	ds_write_b128 v15, v[0:3] offset:16384
	s_waitcnt vmcnt(6)
	ds_write_b128 v15, v[120:123] offset:24576
	s_waitcnt vmcnt(5)
	ds_write_b128 v15, v[124:127] offset:32768
	s_waitcnt vmcnt(4)
	ds_write_b128 v15, v[128:131] offset:40960
	s_waitcnt vmcnt(3)
	ds_write_b128 v15, v[132:135] offset:49152
	s_waitcnt vmcnt(2)
	ds_write_b128 v15, v[136:139] offset:57344
	s_waitcnt vmcnt(1)
	ds_write_b128 v16, v[140:143] offset:49152
	s_waitcnt vmcnt(0)
	ds_write_b128 v16, v[144:147] offset:57344
	v_lshl_add_u64 v[0:1], v[12:13], 0, s[76:77]
	v_lshlrev_b64 v[0:1], 11, v[0:1]
	v_lshl_add_u64 v[0:1], s[14:15], 0, v[0:1]
	v_lshl_add_u64 v[2:3], s[16:17], 2, v[6:7]
	v_lshl_add_u64 v[0:1], v[0:1], 0, v[168:169]
	global_load_dword v13, v[0:1], off
	s_nop 0
	global_load_dword v2, v[2:3], off
	s_movk_i32 s16, 0x1ff
	v_cmp_gt_i32_e32 vcc, s16, v12
	s_waitcnt vmcnt(0)
	v_add_f32_e32 v3, v13, v2
	s_and_saveexec_b64 s[16:17], vcc
	s_cbranch_execz .LBB0_1006
	global_load_dword v0, v[0:1], off offset:3072
	s_waitcnt vmcnt(0)
	v_add_f32_e32 v3, v3, v0

.LBB0_1509:
	s_cmp_lt_u32 s10, s80
	s_cselect_b64 s[44:45], -1, 0
	s_cmp_ge_u32 s10, s80
	s_cbranch_scc1 .LBB0_1511
	v_add_co_u32_e32 v246, vcc, 0x2000000, v94
	s_nop 1
	v_addc_co_u32_e32 v247, vcc, 0, v95, vcc
	global_load_dwordx4 v[84:87], v[94:95], off
	global_load_dwordx4 v[88:91], v[246:247], off
.LBB0_1511:
	s_and_b64 s[0:1], s[92:93], s[42:43]
	s_andn2_b64 vcc, exec, s[0:1]
	s_cbranch_vccnz .LBB0_1513
	v_lshl_add_u32 v143, v100, 13, v153
	ds_read_b128 v[144:147], v143 offset:32768
	s_mov_b64 s[42:43], 0
	s_waitcnt lgkmcnt(0)
	v_mfma_f32_32x32x16_bf16 v[16:31], v[144:147], v[36:39], v[16:31]
	ds_read_b128 v[144:147], v143 offset:33280
	v_add_f32_e32 v48, 0, v48
	v_add_f32_e32 v48, v96, v48
	v_add_f32_e32 v48, v49, v48
	v_add_f32_e32 v48, v104, v48
	s_waitcnt lgkmcnt(0)
	v_mfma_f32_32x32x16_bf16 v[0:15], v[144:147], v[36:39], v[0:15]
	ds_read_b128 v[144:147], v143 offset:34816
	v_add_f32_e32 v48, v50, v48
	v_add_f32_e32 v48, v105, v48
	v_add_f32_e32 v48, v51, v48
	v_add_f32_e32 v48, v106, v48
	s_waitcnt lgkmcnt(0)
	v_mfma_f32_32x32x16_bf16 v[16:31], v[144:147], v[32:35], v[16:31]
	ds_read_b128 v[144:147], v143 offset:35328
	v_add_f32_e32 v48, v52, v48
	v_add_f32_e32 v48, v107, v48
	v_add_f32_e32 v48, v53, v48
	v_add_f32_e32 v48, v108, v48
	s_waitcnt lgkmcnt(0)
	v_mfma_f32_32x32x16_bf16 v[0:15], v[144:147], v[32:35], v[0:15]
	ds_read_b128 v[144:147], v143 offset:36864
	v_add_f32_e32 v48, v54, v48
	v_add_f32_e32 v48, v109, v48
	v_add_f32_e32 v48, v55, v48
	v_add_f32_e32 v48, v110, v48
	s_waitcnt lgkmcnt(0)
	v_mfma_f32_32x32x16_bf16 v[16:31], v[144:147], v[40:43], v[16:31]
	ds_read_b128 v[144:147], v143 offset:37376
	v_add_f32_e32 v48, v56, v48
	v_add_f32_e32 v48, v111, v48
	v_add_f32_e32 v48, v57, v48
	v_add_f32_e32 v48, v136, v48
	s_waitcnt lgkmcnt(0)
	v_mfma_f32_32x32x16_bf16 v[0:15], v[144:147], v[40:43], v[0:15]
	ds_read_b128 v[144:147], v143 offset:38912
	v_add_f32_e32 v48, v58, v48
	v_add_f32_e32 v48, v137, v48
	v_add_f32_e32 v48, v59, v48
	v_add_f32_e32 v48, v138, v48
	s_waitcnt lgkmcnt(0)
	v_mfma_f32_32x32x16_bf16 v[16:31], v[144:147], v[44:47], v[16:31]
	ds_read_b128 v[144:147], v143 offset:39424
	v_add_f32_e32 v48, v60, v48
	v_add_f32_e32 v48, v139, v48
	v_add_f32_e32 v48, v61, v48
	v_add_f32_e32 v48, v140, v48
	s_waitcnt lgkmcnt(0)
	v_mfma_f32_32x32x16_bf16 v[0:15], v[144:147], v[44:47], v[0:15]
	v_add_f32_e32 v48, v62, v48
	v_add_f32_e32 v48, v141, v48
	v_add_f32_e32 v48, v63, v48
	v_add_f32_e32 v48, v142, v48
	v_add_f32_e32 v98, v98, v48

.LBB0_1526:
	v_exp_f32_e32 v48, v48
	v_exp_f32_e32 v96, v32
	v_exp_f32_e32 v49, v49
	v_exp_f32_e32 v104, v33
	v_exp_f32_e32 v50, v50
	v_exp_f32_e32 v105, v34
	v_exp_f32_e32 v51, v51
	v_exp_f32_e32 v106, v35
	v_exp_f32_e32 v52, v52
	v_exp_f32_e32 v107, v36
	v_exp_f32_e32 v53, v53
	v_exp_f32_e32 v108, v37
	v_exp_f32_e32 v54, v54
	v_exp_f32_e32 v109, v38
	v_exp_f32_e32 v55, v55
	v_exp_f32_e32 v110, v39
	v_exp_f32_e32 v56, v56
	v_exp_f32_e32 v111, v40
	v_exp_f32_e32 v57, v57
	v_exp_f32_e32 v136, v41
	v_exp_f32_e32 v58, v58
	v_exp_f32_e32 v137, v42
	v_exp_f32_e32 v59, v59
	v_exp_f32_e32 v138, v43
	v_exp_f32_e32 v60, v60
	v_exp_f32_e32 v139, v44
	v_exp_f32_e32 v61, v61
	v_exp_f32_e32 v140, v45
	v_exp_f32_e32 v62, v62
	v_exp_f32_e32 v141, v46
	v_exp_f32_e32 v63, v63
	v_exp_f32_e32 v142, v47
	v_cvt_pk_bf16_f32 v36, v48, v49
	v_cvt_pk_bf16_f32 v37, v50, v51
	v_cvt_pk_bf16_f32 v38, v52, v53
	v_cvt_pk_bf16_f32 v39, v54, v55
	v_cvt_pk_bf16_f32 v32, v56, v57
	v_cvt_pk_bf16_f32 v33, v58, v59
	v_cvt_pk_bf16_f32 v34, v60, v61
	v_cvt_pk_bf16_f32 v35, v62, v63
	v_cvt_pk_bf16_f32 v40, v96, v104
	v_cvt_pk_bf16_f32 v41, v105, v106
	v_cvt_pk_bf16_f32 v42, v107, v108
	v_cvt_pk_bf16_f32 v43, v109, v110
	v_cvt_pk_bf16_f32 v44, v111, v136
	v_cvt_pk_bf16_f32 v45, v137, v138
	v_cvt_pk_bf16_f32 v46, v139, v140
	s_andn2_b64 vcc, exec, s[94:95]
	v_cvt_pk_bf16_f32 v47, v141, v142
	s_cbranch_vccnz .LBB0_1528
	v_lshl_add_u32 v143, v102, 13, v153
	ds_read_b128 v[144:147], v143 offset:32768
	s_waitcnt lgkmcnt(0)
	v_mfma_f32_32x32x16_bf16 v[16:31], v[144:147], v[36:39], v[16:31]
	ds_read_b128 v[144:147], v143 offset:33280
	v_add_f32_e32 v48, 0, v48
	v_add_f32_e32 v48, v96, v48
	v_add_f32_e32 v48, v49, v48
	v_add_f32_e32 v48, v104, v48
	s_waitcnt lgkmcnt(0)
	v_mfma_f32_32x32x16_bf16 v[0:15], v[144:147], v[36:39], v[0:15]
	ds_read_b128 v[144:147], v143 offset:34816
	v_add_f32_e32 v48, v50, v48
	v_add_f32_e32 v48, v105, v48
	v_add_f32_e32 v48, v51, v48
	v_add_f32_e32 v48, v106, v48
	s_waitcnt lgkmcnt(0)
	v_mfma_f32_32x32x16_bf16 v[16:31], v[144:147], v[32:35], v[16:31]
	ds_read_b128 v[144:147], v143 offset:35328
	v_add_f32_e32 v48, v52, v48
	v_add_f32_e32 v48, v107, v48
	v_add_f32_e32 v48, v53, v48
	v_add_f32_e32 v48, v108, v48
	s_waitcnt lgkmcnt(0)
	v_mfma_f32_32x32x16_bf16 v[0:15], v[144:147], v[32:35], v[0:15]
	ds_read_b128 v[144:147], v143 offset:36864
	v_add_f32_e32 v48, v54, v48
	v_add_f32_e32 v48, v109, v48
	v_add_f32_e32 v48, v55, v48
	v_add_f32_e32 v48, v110, v48
	s_waitcnt lgkmcnt(0)
	v_mfma_f32_32x32x16_bf16 v[16:31], v[144:147], v[40:43], v[16:31]
	ds_read_b128 v[144:147], v143 offset:37376
	v_add_f32_e32 v48, v56, v48
	v_add_f32_e32 v48, v111, v48
	v_add_f32_e32 v48, v57, v48
	v_add_f32_e32 v48, v136, v48
	s_waitcnt lgkmcnt(0)
	v_mfma_f32_32x32x16_bf16 v[0:15], v[144:147], v[40:43], v[0:15]
	ds_read_b128 v[144:147], v143 offset:38912
	v_add_f32_e32 v48, v58, v48
	v_add_f32_e32 v48, v137, v48
	v_add_f32_e32 v48, v59, v48
	v_add_f32_e32 v48, v138, v48
	s_waitcnt lgkmcnt(0)
	v_mfma_f32_32x32x16_bf16 v[16:31], v[144:147], v[44:47], v[16:31]
	ds_read_b128 v[144:147], v143 offset:39424
	v_add_f32_e32 v48, v60, v48
	v_add_f32_e32 v48, v139, v48
	v_add_f32_e32 v48, v61, v48
	v_add_f32_e32 v48, v140, v48
	s_waitcnt lgkmcnt(0)
	v_mfma_f32_32x32x16_bf16 v[0:15], v[144:147], v[44:47], v[0:15]
	v_add_f32_e32 v48, v62, v48
	v_add_f32_e32 v48, v141, v48
	v_add_f32_e32 v48, v63, v48
	v_add_f32_e32 v48, v142, v48
	v_add_f32_e32 v98, v98, v48
	s_branch .LBB0_1530

.LBB0_1530:
	v_add_u32_e32 v248, 1, v102
	v_cmp_ne_u32_e64 s[0:1], 2, v102
	v_xor_b32_e32 v101, 1, v101
	s_andn2_b64 vcc, exec, s[44:45]
	v_cndmask_b32_e64 v102, 0, v248, s[0:1]
	s_cbranch_vccnz .LBB0_1508
	v_lshl_add_u32 v249, v101, 13, v151
	v_lshl_add_u32 v248, v102, 13, v152
	s_waitcnt vmcnt(1)
	ds_write_b128 v249, v[84:87]
	s_waitcnt vmcnt(0)
	ds_write_b128 v248, v[88:91] offset:32768
	s_branch .LBB0_1508
.LBB0_1532:
	s_and_b64 s[0:1], s[92:93], s[42:43]
	s_and_b64 vcc, exec, s[0:1]
	s_cbranch_vccz .LBB0_1534
	v_lshl_add_u32 v143, v100, 13, v153
	ds_read_b128 v[144:147], v143 offset:32768
	s_waitcnt lgkmcnt(0)
	v_mfma_f32_32x32x16_bf16 v[16:31], v[144:147], v[36:39], v[16:31]
	ds_read_b128 v[144:147], v143 offset:33280
	v_add_f32_e32 v48, 0, v48
	v_add_f32_e32 v48, v96, v48
	v_add_f32_e32 v48, v49, v48
	v_add_f32_e32 v48, v104, v48
	s_waitcnt lgkmcnt(0)
	v_mfma_f32_32x32x16_bf16 v[0:15], v[144:147], v[36:39], v[0:15]
	ds_read_b128 v[144:147], v143 offset:34816
	v_add_f32_e32 v48, v50, v48
	v_add_f32_e32 v48, v105, v48
	v_add_f32_e32 v48, v51, v48
	v_add_f32_e32 v48, v106, v48
	s_waitcnt lgkmcnt(0)
	v_mfma_f32_32x32x16_bf16 v[16:31], v[144:147], v[32:35], v[16:31]
	ds_read_b128 v[144:147], v143 offset:35328
	v_add_f32_e32 v48, v52, v48
	v_add_f32_e32 v48, v107, v48
	v_add_f32_e32 v48, v53, v48
	v_add_f32_e32 v48, v108, v48
	s_waitcnt lgkmcnt(0)
	v_mfma_f32_32x32x16_bf16 v[0:15], v[144:147], v[32:35], v[0:15]
	ds_read_b128 v[144:147], v143 offset:36864
	v_add_f32_e32 v48, v54, v48
	v_add_f32_e32 v48, v109, v48
	v_add_f32_e32 v48, v55, v48
	v_add_f32_e32 v48, v110, v48
	s_waitcnt lgkmcnt(0)
	v_mfma_f32_32x32x16_bf16 v[16:31], v[144:147], v[40:43], v[16:31]
	ds_read_b128 v[144:147], v143 offset:37376
	v_add_f32_e32 v48, v56, v48
	v_add_f32_e32 v48, v111, v48
	v_add_f32_e32 v48, v57, v48
	v_add_f32_e32 v48, v136, v48
	s_waitcnt lgkmcnt(0)
	v_mfma_f32_32x32x16_bf16 v[0:15], v[144:147], v[40:43], v[0:15]
	ds_read_b128 v[144:147], v143 offset:38912
	v_add_f32_e32 v48, v58, v48
	v_add_f32_e32 v48, v137, v48
	v_add_f32_e32 v48, v59, v48
	v_add_f32_e32 v48, v138, v48
	s_waitcnt lgkmcnt(0)
	v_mfma_f32_32x32x16_bf16 v[16:31], v[144:147], v[44:47], v[16:31]
	ds_read_b128 v[144:147], v143 offset:39424
	v_add_f32_e32 v48, v60, v48
	v_add_f32_e32 v48, v139, v48
	v_add_f32_e32 v48, v61, v48
	v_add_f32_e32 v48, v140, v48
	s_waitcnt lgkmcnt(0)
	v_mfma_f32_32x32x16_bf16 v[0:15], v[144:147], v[44:47], v[0:15]
	v_add_f32_e32 v48, v62, v48
	v_add_f32_e32 v48, v141, v48
	v_add_f32_e32 v48, v63, v48
	v_add_f32_e32 v48, v142, v48
	v_add_f32_e32 v98, v98, v48
